# v92 plus per-wave-half placement of the attention DMA issue block (priority waves behind their last QK MFMA, others at the tile top)
# baseline (speedup 1.0000x reference)
.LBB0_106:
	v_mov_b32_e32 v14, v0
	v_mov_b32_e32 v15, v0
	s_waitcnt vmcnt(0) lgkmcnt(0)
	s_barrier
	v_mov_b32_e32 v1, v0
	v_mov_b32_e32 v2, v0
	v_mov_b32_e32 v3, v0
	v_mov_b32_e32 v4, v0
	v_mov_b32_e32 v5, v0
	v_mov_b32_e32 v6, v0
	v_mov_b32_e32 v7, v0
	v_mov_b32_e32 v8, v0
	v_mov_b32_e32 v9, v0
	v_mov_b32_e32 v10, v0
	v_mov_b32_e32 v11, v0
	v_mov_b32_e32 v12, v0
	v_mov_b32_e32 v13, v0
	s_lshl_b32 s30, s43, 12
	s_lshl_b32 s44, s48, 7
	v_mov_b64_e32 v[62:63], v[14:15]
	v_mov_b64_e32 v[46:47], v[14:15]
	v_mov_b64_e32 v[30:31], v[14:15]
	s_add_i32 s43, s30, 0xffffff80
	v_add_u32_e32 v153, s44, v171
	v_add_u32_e32 v155, s44, v172
	s_add_i32 s45, s46, 0x80
	s_mov_b32 s50, 2
	s_mov_b32 s51, 1
	s_mov_b32 s53, 0
	v_mov_b32_e32 v157, 0
	v_mov_b32_e32 v159, 0
	v_mov_b32_e32 v96, 0
	v_mov_b32_e32 v97, 0
	v_mov_b32_e32 v98, 0
	v_mov_b32_e32 v99, 0
	v_mov_b32_e32 v100, 0
	v_mov_b32_e32 v101, 0
	v_mov_b32_e32 v102, 0
	v_mov_b32_e32 v103, 0
	v_mov_b32_e32 v104, 0
	v_mov_b32_e32 v105, 0
	v_mov_b32_e32 v106, 0
	v_mov_b32_e32 v107, 0
	v_mov_b32_e32 v108, 0
	v_mov_b32_e32 v109, 0
	v_mov_b32_e32 v110, 0
	v_mov_b32_e32 v111, 0
	v_mov_b64_e32 v[60:61], v[12:13]
	v_mov_b64_e32 v[58:59], v[10:11]
	v_mov_b64_e32 v[56:57], v[8:9]
	v_mov_b64_e32 v[54:55], v[6:7]
	v_mov_b64_e32 v[52:53], v[4:5]
	v_mov_b64_e32 v[50:51], v[2:3]
	v_mov_b64_e32 v[48:49], v[0:1]
	v_mov_b64_e32 v[44:45], v[12:13]
	v_mov_b64_e32 v[42:43], v[10:11]
	v_mov_b64_e32 v[40:41], v[8:9]
	v_mov_b64_e32 v[38:39], v[6:7]
	v_mov_b64_e32 v[36:37], v[4:5]
	v_mov_b64_e32 v[34:35], v[2:3]
	v_mov_b64_e32 v[32:33], v[0:1]
	v_mov_b64_e32 v[28:29], v[12:13]
	v_mov_b64_e32 v[26:27], v[10:11]
	v_mov_b64_e32 v[24:25], v[8:9]
	v_mov_b64_e32 v[22:23], v[6:7]
	v_mov_b64_e32 v[20:21], v[4:5]
	v_mov_b64_e32 v[18:19], v[2:3]
	v_mov_b64_e32 v[16:17], v[0:1]
	s_mov_b32 s52, 0
	s_waitcnt vmcnt(0)
	s_mul_i32 s30, s53, 0x2400
	v_add_u32_e32 v242, s30, v173
	s_mul_i32 s30, s53, 0x4800
	v_add_u32_e32 v243, s30, v174
	s_mov_b32 s58, 0xff800000
	v_readfirstlane_b32 s99, v191
	s_lshr_b32 s99, s99, 8
	v_readfirstlane_b32 s30, v191
	s_lshr_b32 s30, s30, 8
	s_cmp_eq_u32 s30, 0
	s_cbranch_scc1 .Latt_diff_p0
	s_setprio 1

.Latt_diff_dmaendB:
	v_max3_f32 v227, v64, v65, v66
	v_max3_f32 v228, v67, v68, v69
	v_max3_f32 v227, v227, v70, v71
	v_max3_f32 v228, v228, v72, v73
	v_max3_f32 v227, v227, v74, v75
	v_max3_f32 v228, v228, v76, v77
	v_max3_f32 v227, v227, v78, v79
	v_max3_f32 v229, v80, v81, v82
	v_max3_f32 v226, v83, v84, v85
	v_max3_f32 v229, v229, v86, v87
	v_max3_f32 v226, v226, v88, v89
	v_max3_f32 v229, v229, v90, v91
	v_max3_f32 v226, v226, v92, v93
	v_max3_f32 v229, v229, v94, v95
	v_max3_f32 v226, v226, v227, v228
	v_max_f32_e32 v226, v226, v229
	v_cmp_lt_f32_e32 vcc, s58, v226
	s_cbranch_vccnz .Latt_diff_rare

.LBB0_177:
	v_mov_b32_e32 v14, v0
	v_mov_b32_e32 v15, v0
	s_waitcnt vmcnt(0) lgkmcnt(0)
	s_barrier
	v_mov_b32_e32 v1, v0
	v_mov_b32_e32 v2, v0
	v_mov_b32_e32 v3, v0
	v_mov_b32_e32 v4, v0
	v_mov_b32_e32 v5, v0
	v_mov_b32_e32 v6, v0
	v_mov_b32_e32 v7, v0
	v_mov_b32_e32 v8, v0
	v_mov_b32_e32 v9, v0
	v_mov_b32_e32 v10, v0
	v_mov_b32_e32 v11, v0
	v_mov_b32_e32 v12, v0
	v_mov_b32_e32 v13, v0
	s_lshl_b32 s49, s49, 12
	v_mov_b64_e32 v[30:31], v[14:15]
	v_mov_b64_e32 v[46:47], v[14:15]
	v_mov_b64_e32 v[62:63], v[14:15]
	v_mad_u64_u32 v[222:223], s[30:31], s50, v238, v[190:191]
	v_mad_u64_u32 v[224:225], s[30:31], s50, v240, v[192:193]
	v_mad_u64_u32 v[226:227], s[30:31], s50, v242, v[194:195]
	v_mad_u64_u32 v[228:229], s[30:31], s50, v244, v[196:197]
	s_addk_i32 s49, 0xff80
	s_add_i32 s51, s60, 0x80
	s_mov_b32 s52, 2
	s_mov_b32 s53, 1
	s_mov_b32 s56, 0
	v_mov_b32_e32 v205, 0
	v_mov_b32_e32 v207, 0
	v_mov_b32_e32 v96, 0
	v_mov_b32_e32 v97, 0
	v_mov_b32_e32 v98, 0
	v_mov_b32_e32 v99, 0
	v_mov_b32_e32 v100, 0
	v_mov_b32_e32 v101, 0
	v_mov_b32_e32 v102, 0
	v_mov_b32_e32 v103, 0
	v_mov_b32_e32 v104, 0
	v_mov_b32_e32 v105, 0
	v_mov_b32_e32 v106, 0
	v_mov_b32_e32 v107, 0
	v_mov_b32_e32 v108, 0
	v_mov_b32_e32 v109, 0
	v_mov_b32_e32 v110, 0
	v_mov_b32_e32 v111, 0
	v_mov_b64_e32 v[28:29], v[12:13]
	v_mov_b64_e32 v[26:27], v[10:11]
	v_mov_b64_e32 v[24:25], v[8:9]
	v_mov_b64_e32 v[22:23], v[6:7]
	v_mov_b64_e32 v[20:21], v[4:5]
	v_mov_b64_e32 v[18:19], v[2:3]
	v_mov_b64_e32 v[16:17], v[0:1]
	v_mov_b64_e32 v[44:45], v[12:13]
	v_mov_b64_e32 v[42:43], v[10:11]
	v_mov_b64_e32 v[40:41], v[8:9]
	v_mov_b64_e32 v[38:39], v[6:7]
	v_mov_b64_e32 v[36:37], v[4:5]
	v_mov_b64_e32 v[34:35], v[2:3]
	v_mov_b64_e32 v[32:33], v[0:1]
	v_mov_b64_e32 v[60:61], v[12:13]
	v_mov_b64_e32 v[58:59], v[10:11]
	v_mov_b64_e32 v[56:57], v[8:9]
	v_mov_b64_e32 v[54:55], v[6:7]
	v_mov_b64_e32 v[52:53], v[4:5]
	v_mov_b64_e32 v[50:51], v[2:3]
	v_mov_b64_e32 v[48:49], v[0:1]
	s_mov_b32 s55, 0
	s_waitcnt vmcnt(0)
	s_mul_i32 s30, s56, 0x6400
	v_add_u32_e32 v209, s30, v246
	s_mul_i32 s30, s56, 0x4800
	v_add_u32_e32 v219, s30, v247
	s_mov_b32 s58, 0xff800000
	v_readfirstlane_b32 s99, v191
	s_lshr_b32 s99, s99, 8
	v_readfirstlane_b32 s30, v191
	s_lshr_b32 s30, s30, 8
	s_cmp_eq_u32 s30, 0
	s_cbranch_scc1 .Latt_mla_p0
	s_setprio 1

.Latt_mla_dmaendB:
	s_nop 6
	v_max3_f32 v215, v80, v81, v82
	v_max3_f32 v209, v83, v84, v85
	v_max3_f32 v215, v215, v86, v87
	v_max3_f32 v209, v209, v88, v89
	v_max3_f32 v215, v215, v90, v91
	v_max3_f32 v209, v209, v92, v93
	v_max3_f32 v215, v215, v94, v95
	v_max3_f32 v209, v209, v211, v213
	v_max_f32_e32 v209, v209, v215
	v_cmp_lt_f32_e32 vcc, s58, v209
	s_cbranch_vccnz .Latt_mla_rare
